# speedup vs baseline: 1.0242x; 1.0010x over previous
; __device__ __forceinline__ float bflo(unsigned w) { return __uint_as_float(w << 16); }
; __device__ __forceinline__ float bfhi(unsigned w) { return __uint_as_float(w & 0xffff0000u); }
; template <int MODE, bool PRE = false, bool NEXT = false> ...
;     ...
;       } else if constexpr (MODE == EP_RES) {
;         float* orow = (float*)e.out + (long)row * e.ldo + cbase;
;         const float* arow = (const float*)e.aux + (long)row * e.ldaux + cbase;
;         const u16* brow = (const u16*)e.aux + (long)row * e.ldaux + cbase;
;         u16* xrow = e.xb + (long)row * 1024 + cbase;
;         float part = 0.f;
; #pragma unroll
;         for (int bj = 0; bj < 2; ++bj)
; #pragma unroll
;           for (int n = 0; n < 2; ++n) {
;             f32x4 a;
;             if (e.auxbf) { const u32x2 w = *reinterpret_cast<const u32x2*>(brow + bj * 128 + n * 16); a = f32x4{bflo(w[0]), bfhi(w[0]), bflo(w[1]), bfhi(w[1])}; }
;             else a = *reinterpret_cast<const f32x4*>(arow + bj * 128 + n * 16);
;             a += acc[ai][bj][m][n];
;             if (e.out) *reinterpret_cast<f32x4*>(orow + bj * 128 + n * 16) = a;
;             if (e.xb) {
;               u32x2 w = {cvtpk(a[0], a[1]), cvtpk(a[2], a[3])};
;               *reinterpret_cast<u32x2*>(xrow + bj * 128 + n * 16) = w;
;               part += a[0] * a[0] + a[1] * a[1] + a[2] * a[2] + a[3] * a[3];
;             }
;           }
;         if (e.xb) {
;           part += __int_as_float(__builtin_amdgcn_ds_bpermute((lane ^ 16) << 2, __float_as_int(part)));
;           part += __int_as_float(__builtin_amdgcn_ds_bpermute((lane ^ 32) << 2, __float_as_int(part)));
;           if (fq == 0) reinterpret_cast<float*>(g_lds)[row * 4 + wc] = part;
;         }
.LBB0_653:
	s_lshl_b64 s[10:11], s[8:9], 1
	v_readlane_b32 s12, v253, 58
	s_add_u32 s14, s12, s10
	v_readlane_b32 s10, v253, 59
	s_addc_u32 s15, s10, s11
	s_lshl_b32 s12, s0, 8
	s_ashr_i32 s13, s12, 31
	s_lshl_b64 s[10:11], s[12:13], 1
	s_add_u32 s10, s14, s10
	s_addc_u32 s11, s15, s11
	s_lshl_b64 s[8:9], s[8:9], 2
	v_readlane_b32 s14, v252, 41
	v_readlane_b32 s15, v252, 42
	s_add_u32 s14, s14, s8
	s_addc_u32 s15, s15, s9
	s_lshl_b64 s[8:9], s[12:13], 2
	s_add_u32 s12, s14, s8
	s_addc_u32 s13, s15, s9
	v_readlane_b32 s8, v252, 38
	v_readlane_b32 s9, v252, 39
	s_and_b64 s[8:9], s[8:9], exec
	s_cselect_b32 s8, s12, s10
	v_readfirstlane_b32 s12, v134
	v_lshrrev_b32_e32 v0, 2, v134
	s_cselect_b32 s9, s13, s11
	s_bfe_u32 s58, s12, 0x20006
	v_and_b32_e32 v0, 12, v0
	v_lshl_or_b32 v130, s58, 5, v0
	v_mov_b32_e32 v0, 1.0
	s_ashr_i32 s12, s12, 2
	v_lshlrev_b32_e32 v0, 2, v130
	s_andn2_b32 s12, s12, 63
	v_lshl_add_u64 v[136:137], s[8:9], 0, v[0:1]
	v_lshlrev_b32_e32 v0, 1, v130
	v_or_b32_e32 v138, s12, v142
	v_sub_co_u32_e32 v130, vcc, 0, v0
	v_readlane_b32 s12, v252, 43
	s_nop 0
	v_subb_co_u32_e64 v131, s[8:9], 0, 0, vcc
	v_ashrrev_i32_e32 v139, 31, v138
	v_readlane_b32 s13, v252, 44
	v_lshl_add_u64 v[140:141], v[136:137], 0, v[130:131]
	v_lshlrev_b64 v[144:145], 11, v[138:139]
	v_cndmask_b32_e64 v130, 0, 1, s[12:13]
	v_lshl_add_u64 v[146:147], v[140:141], 0, v[144:145]
	v_cmp_ne_u32_e64 s[8:9], 1, v130
	s_and_b64 vcc, exec, s[12:13]
	s_cbranch_vccz .Lpg_pf_done
	v_mov_b32_e32 v152, v138
	v_ashrrev_i32_e32 v153, 31, v152
	v_lshlrev_b64 v[154:155], 11, v[152:153]
	v_lshl_add_u64 v[154:155], v[140:141], 0, v[154:155]
	global_load_dwordx2 v[192:193], v[154:155], off
	global_load_dwordx2 v[194:195], v[154:155], off offset:32
	global_load_dwordx2 v[196:197], v[154:155], off offset:256
	global_load_dwordx2 v[198:199], v[154:155], off offset:288
	v_or_b32_e32 v152, 16, v138
	v_ashrrev_i32_e32 v153, 31, v152
	v_lshlrev_b64 v[154:155], 11, v[152:153]
	v_lshl_add_u64 v[154:155], v[140:141], 0, v[154:155]
	global_load_dwordx2 v[200:201], v[154:155], off
	global_load_dwordx2 v[202:203], v[154:155], off offset:32
	global_load_dwordx2 v[204:205], v[154:155], off offset:256
	global_load_dwordx2 v[206:207], v[154:155], off offset:288
	v_or_b32_e32 v152, 32, v138
	v_ashrrev_i32_e32 v153, 31, v152
	v_lshlrev_b64 v[154:155], 11, v[152:153]
	v_lshl_add_u64 v[154:155], v[140:141], 0, v[154:155]
	global_load_dwordx2 v[208:209], v[154:155], off
	global_load_dwordx2 v[210:211], v[154:155], off offset:32
	global_load_dwordx2 v[212:213], v[154:155], off offset:256
	global_load_dwordx2 v[214:215], v[154:155], off offset:288
	v_or_b32_e32 v152, 48, v138
	v_ashrrev_i32_e32 v153, 31, v152
	v_lshlrev_b64 v[154:155], 11, v[152:153]
	v_lshl_add_u64 v[154:155], v[140:141], 0, v[154:155]
	global_load_dwordx2 v[216:217], v[154:155], off
	global_load_dwordx2 v[218:219], v[154:155], off offset:32
	global_load_dwordx2 v[220:221], v[154:155], off offset:256
	global_load_dwordx2 v[222:223], v[154:155], off offset:288
	v_add_u32_e32 v152, 0x80, v138
	v_ashrrev_i32_e32 v153, 31, v152
	v_lshlrev_b64 v[154:155], 11, v[152:153]
	v_lshl_add_u64 v[154:155], v[140:141], 0, v[154:155]
	global_load_dwordx2 v[224:225], v[154:155], off
	global_load_dwordx2 v[226:227], v[154:155], off offset:32
	global_load_dwordx2 v[228:229], v[154:155], off offset:256
	global_load_dwordx2 v[230:231], v[154:155], off offset:288
	v_add_u32_e32 v152, 0x90, v138
	v_ashrrev_i32_e32 v153, 31, v152
	v_lshlrev_b64 v[154:155], 11, v[152:153]
	v_lshl_add_u64 v[154:155], v[140:141], 0, v[154:155]
	global_load_dwordx2 v[232:233], v[154:155], off
	global_load_dwordx2 v[234:235], v[154:155], off offset:32
	global_load_dwordx2 v[236:237], v[154:155], off offset:256
	global_load_dwordx2 v[238:239], v[154:155], off offset:288
	v_add_u32_e32 v152, 0xa0, v138
	v_ashrrev_i32_e32 v153, 31, v152
	v_lshlrev_b64 v[154:155], 11, v[152:153]
	v_lshl_add_u64 v[154:155], v[140:141], 0, v[154:155]
	global_load_dwordx2 v[240:241], v[154:155], off
	global_load_dwordx2 v[242:243], v[154:155], off offset:32
	global_load_dwordx2 v[244:245], v[154:155], off offset:256
	global_load_dwordx2 v[246:247], v[154:155], off offset:288
	v_add_u32_e32 v152, 0xb0, v138
	v_ashrrev_i32_e32 v153, 31, v152
	v_lshlrev_b64 v[154:155], 11, v[152:153]
	v_lshl_add_u64 v[154:155], v[140:141], 0, v[154:155]
	global_load_dwordx2 v[248:249], v[154:155], off
	global_load_dwordx2 v[250:251], v[154:155], off offset:32
	global_load_dwordx2 v[182:183], v[154:155], off offset:256
	global_load_dwordx2 v[184:185], v[154:155], off offset:288
	s_waitcnt vmcnt(0)
.Lpg_pf_done:
	s_andn2_b64 vcc, exec, s[12:13]
	s_mov_b64 s[12:13], -1
	s_mov_b32 s59, 0x42b504f3
	s_cbranch_vccnz .LBB0_655
	v_mov_b64_e32 v[132:133], v[192:193]
	s_mov_b64 s[12:13], 0
	v_lshlrev_b32_e32 v130, 16, v132
	v_and_b32_e32 v131, 0xffff0000, v132
	v_lshlrev_b32_e32 v132, 16, v133
	v_and_b32_e32 v133, 0xffff0000, v133
.LBB0_655:
	v_lshlrev_b64 v[142:143], 12, v[138:139]
	s_andn2_b64 vcc, exec, s[12:13]
	v_lshl_add_u64 v[148:149], v[136:137], 0, v[142:143]
	s_cbranch_vccnz .LBB0_657
	global_load_dwordx4 v[130:133], v[148:149], off
	s_waitcnt vmcnt(0)
.LBB0_657:
	v_readlane_b32 s12, v254, 57
	v_readlane_b32 s13, v254, 58
	v_lshl_add_u64 v[142:143], s[10:11], 0, v[0:1]
	s_andn2_b64 vcc, exec, s[12:13]
	v_cndmask_b32_e64 v0, 0, 1, s[12:13]
	v_cmp_ne_u32_e64 s[10:11], 1, v0
	v_lshl_add_u64 v[144:145], v[142:143], 0, v[144:145]
	s_cbranch_vccnz .LBB0_861
	v_pk_add_f32 v[126:127], v[126:127], v[130:131]
	v_pk_add_f32 v[128:129], v[128:129], v[132:133]
	v_cvt_pk_bf16_f32 v130, v126, v127
	v_pk_mul_f32 v[126:127], v[126:127], v[126:127]
	v_cvt_pk_bf16_f32 v131, v128, v129
	v_pk_mul_f32 v[128:129], v[128:129], v[128:129]
	v_add_f32_e32 v0, v126, v127
	v_add_f32_e32 v0, v128, v0
	global_store_dwordx2 v[144:145], v[130:131], off
	v_add_f32_e32 v130, v129, v0
	s_and_b64 vcc, exec, s[8:9]
	s_mov_b64 s[12:13], -1
	s_cbranch_vccnz .LBB0_660
.LBB0_659:
	v_mov_b64_e32 v[128:129], v[194:195]
	s_mov_b64 s[12:13], 0
	v_lshlrev_b32_e32 v126, 16, v128
	v_and_b32_e32 v127, 0xffff0000, v128
	v_lshlrev_b32_e32 v128, 16, v129
	v_and_b32_e32 v129, 0xffff0000, v129

; template <int MODE, bool PRE = false, bool NEXT = false> ...
;     ...
;             a += acc[ai][bj][m][n];
;             if (e.out) *reinterpret_cast<f32x4*>(orow + bj * 128 + n * 16) = a;
;             if (e.xb) {
;               u32x2 w = {cvtpk(a[0], a[1]), cvtpk(a[2], a[3])};
;               *reinterpret_cast<u32x2*>(xrow + bj * 128 + n * 16) = w;
;               part += a[0] * a[0] + a[1] * a[1] + a[2] * a[2] + a[3] * a[3];
.LBB0_662:
	v_pk_add_f32 v[122:123], v[122:123], v[126:127]
	v_pk_add_f32 v[124:125], v[124:125], v[128:129]
	v_cvt_pk_bf16_f32 v126, v122, v123
	v_pk_mul_f32 v[122:123], v[122:123], v[122:123]
	v_cvt_pk_bf16_f32 v127, v124, v125
	v_pk_mul_f32 v[124:125], v[124:125], v[124:125]
	v_add_f32_e32 v0, v122, v123
	v_add_f32_e32 v0, v124, v0
	v_add_f32_e32 v0, v125, v0
	v_add_f32_e32 v130, v130, v0
	global_store_dwordx2 v[144:145], v[126:127], off offset:32

; __device__ __forceinline__ float bflo(unsigned w) { return __uint_as_float(w << 16); }
; __device__ __forceinline__ float bfhi(unsigned w) { return __uint_as_float(w & 0xffff0000u); }
; template <int MODE, bool PRE = false, bool NEXT = false> ...
;     ...
;             if (e.auxbf) { const u32x2 w = *reinterpret_cast<const u32x2*>(brow + bj * 128 + n * 16); a = f32x4{bflo(w[0]), bfhi(w[0]), bflo(w[1]), bfhi(w[1])}; }
;             else a = *reinterpret_cast<const f32x4*>(arow + bj * 128 + n * 16);
;             a += acc[ai][bj][m][n];
;             if (e.out) *reinterpret_cast<f32x4*>(orow + bj * 128 + n * 16) = a;
;             if (e.xb) {
;               u32x2 w = {cvtpk(a[0], a[1]), cvtpk(a[2], a[3])};
;               *reinterpret_cast<u32x2*>(xrow + bj * 128 + n * 16) = w;
;               part += a[0] * a[0] + a[1] * a[1] + a[2] * a[2] + a[3] * a[3];
;             }
;           }
;         if (e.xb) {
;           part += __int_as_float(__builtin_amdgcn_ds_bpermute((lane ^ 16) << 2, __float_as_int(part)));
;           part += __int_as_float(__builtin_amdgcn_ds_bpermute((lane ^ 32) << 2, __float_as_int(part)));
;           if (fq == 0) reinterpret_cast<float*>(g_lds)[row * 4 + wc] = part;
.LBB0_666:
	v_pk_add_f32 v[118:119], v[118:119], v[122:123]
	v_pk_add_f32 v[120:121], v[120:121], v[124:125]
	v_cvt_pk_bf16_f32 v122, v118, v119
	v_pk_mul_f32 v[118:119], v[118:119], v[118:119]
	v_cvt_pk_bf16_f32 v123, v120, v121
	v_pk_mul_f32 v[120:121], v[120:121], v[120:121]
	v_add_f32_e32 v0, v118, v119
	v_add_f32_e32 v0, v120, v0
	v_add_f32_e32 v0, v121, v0
	v_add_f32_e32 v130, v130, v0
	global_store_dwordx2 v[144:145], v[122:123], off offset:256
.LBB0_667:
	s_and_b64 vcc, exec, s[8:9]
	s_mov_b64 s[12:13], -1
	s_cbranch_vccnz .LBB0_669
	v_mov_b64_e32 v[120:121], v[198:199]
	s_mov_b64 s[12:13], 0
	v_lshlrev_b32_e32 v118, 16, v120
	v_and_b32_e32 v119, 0xffff0000, v120
	v_lshlrev_b32_e32 v120, 16, v121
	v_and_b32_e32 v121, 0xffff0000, v121
.LBB0_669:
	s_andn2_b64 vcc, exec, s[12:13]
	s_cbranch_vccnz .LBB0_671
	global_load_dwordx4 v[118:121], v[148:149], off offset:576
	s_waitcnt vmcnt(0)
.LBB0_671:
	v_and_b32_e32 v122, 63, v134
	s_lshl_b32 s12, s58, 2
	v_lshlrev_b32_e32 v0, 2, v122
	s_add_i32 s58, s12, 16
	v_xor_b32_e32 v126, 64, v0
	v_xor_b32_e32 v0, 0x80, v0
	s_and_b64 vcc, exec, s[10:11]
	v_cmp_gt_u32_e64 s[12:13], 16, v122
	s_cbranch_vccnz .LBB0_675
	v_pk_add_f32 v[118:119], v[114:115], v[118:119]
	v_pk_add_f32 v[116:117], v[116:117], v[120:121]
	v_mul_f32_e32 v114, v119, v119
	v_fmac_f32_e32 v114, v118, v118
	v_fmac_f32_e32 v114, v116, v116
	v_fmac_f32_e32 v114, v117, v117
	v_add_f32_e32 v114, v130, v114
	ds_bpermute_b32 v115, v126, v114
	v_cvt_pk_bf16_f32 v118, v118, v119
	v_cvt_pk_bf16_f32 v119, v116, v117
	global_store_dwordx2 v[144:145], v[118:119], off offset:288
	s_waitcnt lgkmcnt(0)
	v_add_f32_e32 v114, v114, v115
	ds_bpermute_b32 v115, v0, v114
	s_and_saveexec_b64 s[64:65], s[12:13]
	s_cbranch_execz .LBB0_674
	s_waitcnt lgkmcnt(0)
	v_add_f32_e32 v114, v114, v115
	v_lshl_add_u32 v115, v138, 4, s58
	ds_write_b32 v115, v114

; __device__ __forceinline__ float bflo(unsigned w) { return __uint_as_float(w << 16); }
; __device__ __forceinline__ float bfhi(unsigned w) { return __uint_as_float(w & 0xffff0000u); }
; template <int MODE, bool PRE = false, bool NEXT = false> ...
;     ...
;             if (e.auxbf) { const u32x2 w = *reinterpret_cast<const u32x2*>(brow + bj * 128 + n * 16); a = f32x4{bflo(w[0]), bfhi(w[0]), bflo(w[1]), bfhi(w[1])}; }
;             else a = *reinterpret_cast<const f32x4*>(arow + bj * 128 + n * 16);
;             a += acc[ai][bj][m][n];
;             if (e.out) *reinterpret_cast<f32x4*>(orow + bj * 128 + n * 16) = a;
;             if (e.xb) {
;               u32x2 w = {cvtpk(a[0], a[1]), cvtpk(a[2], a[3])};
;               *reinterpret_cast<u32x2*>(xrow + bj * 128 + n * 16) = w;
;               part += a[0] * a[0] + a[1] * a[1] + a[2] * a[2] + a[3] * a[3];
.LBB0_678:
	s_waitcnt lgkmcnt(0)
	v_pk_add_f32 v[110:111], v[110:111], v[114:115]
	v_pk_add_f32 v[112:113], v[112:113], v[116:117]
	v_cvt_pk_bf16_f32 v114, v110, v111
	v_pk_mul_f32 v[110:111], v[110:111], v[110:111]
	v_cvt_pk_bf16_f32 v115, v112, v113
	v_pk_mul_f32 v[112:113], v[112:113], v[112:113]
	v_add_f32_e32 v110, v110, v111
	v_add_f32_e32 v110, v112, v110
	global_store_dwordx2 v[120:121], v[114:115], off
	v_add_f32_e32 v114, v113, v110
	s_and_b64 vcc, exec, s[8:9]
	s_mov_b64 s[64:65], -1
	s_cbranch_vccnz .LBB0_680
.LBB0_679:
	v_mov_b64_e32 v[112:113], v[202:203]
	s_mov_b64 s[64:65], 0
	v_lshlrev_b32_e32 v110, 16, v112
	v_and_b32_e32 v111, 0xffff0000, v112
	v_lshlrev_b32_e32 v112, 16, v113
	v_and_b32_e32 v113, 0xffff0000, v113

; template <int MODE, bool PRE = false, bool NEXT = false> ...
;     ...
;             a += acc[ai][bj][m][n];
;             if (e.out) *reinterpret_cast<f32x4*>(orow + bj * 128 + n * 16) = a;
;             if (e.xb) {
;               u32x2 w = {cvtpk(a[0], a[1]), cvtpk(a[2], a[3])};
;               *reinterpret_cast<u32x2*>(xrow + bj * 128 + n * 16) = w;
;               part += a[0] * a[0] + a[1] * a[1] + a[2] * a[2] + a[3] * a[3];
.LBB0_682:
	v_pk_add_f32 v[106:107], v[106:107], v[110:111]
	v_pk_add_f32 v[108:109], v[108:109], v[112:113]
	v_cvt_pk_bf16_f32 v110, v106, v107
	v_pk_mul_f32 v[106:107], v[106:107], v[106:107]
	v_cvt_pk_bf16_f32 v111, v108, v109
	v_pk_mul_f32 v[108:109], v[108:109], v[108:109]
	v_add_f32_e32 v106, v106, v107
	v_add_f32_e32 v106, v108, v106
	v_add_f32_e32 v106, v109, v106
	v_add_f32_e32 v114, v114, v106
	global_store_dwordx2 v[120:121], v[110:111], off offset:32

; template <int MODE, bool PRE = false, bool NEXT = false> ...
;     ...
;             a += acc[ai][bj][m][n];
;             if (e.out) *reinterpret_cast<f32x4*>(orow + bj * 128 + n * 16) = a;
;             if (e.xb) {
;               u32x2 w = {cvtpk(a[0], a[1]), cvtpk(a[2], a[3])};
;               *reinterpret_cast<u32x2*>(xrow + bj * 128 + n * 16) = w;
;               part += a[0] * a[0] + a[1] * a[1] + a[2] * a[2] + a[3] * a[3];
.LBB0_686:
	v_pk_add_f32 v[102:103], v[102:103], v[106:107]
	v_pk_add_f32 v[104:105], v[104:105], v[108:109]
	v_cvt_pk_bf16_f32 v106, v102, v103
	v_pk_mul_f32 v[102:103], v[102:103], v[102:103]
	v_cvt_pk_bf16_f32 v107, v104, v105
	v_pk_mul_f32 v[104:105], v[104:105], v[104:105]
	v_add_f32_e32 v102, v102, v103
	v_add_f32_e32 v102, v104, v102
	v_add_f32_e32 v102, v105, v102
	v_add_f32_e32 v114, v114, v102
	global_store_dwordx2 v[120:121], v[106:107], off offset:256

; __device__ __forceinline__ float bflo(unsigned w) { return __uint_as_float(w << 16); }
; __device__ __forceinline__ float bfhi(unsigned w) { return __uint_as_float(w & 0xffff0000u); }
; template <int MODE, bool PRE = false, bool NEXT = false> ...
;     ...
;             if (e.auxbf) { const u32x2 w = *reinterpret_cast<const u32x2*>(brow + bj * 128 + n * 16); a = f32x4{bflo(w[0]), bfhi(w[0]), bflo(w[1]), bfhi(w[1])}; }
;             else a = *reinterpret_cast<const f32x4*>(arow + bj * 128 + n * 16);
;             a += acc[ai][bj][m][n];
;             if (e.out) *reinterpret_cast<f32x4*>(orow + bj * 128 + n * 16) = a;
;             if (e.xb) {
;               u32x2 w = {cvtpk(a[0], a[1]), cvtpk(a[2], a[3])};
;               *reinterpret_cast<u32x2*>(xrow + bj * 128 + n * 16) = w;
;               part += a[0] * a[0] + a[1] * a[1] + a[2] * a[2] + a[3] * a[3];
;             }
;           }
;         if (e.xb) {
;           part += __int_as_float(__builtin_amdgcn_ds_bpermute((lane ^ 16) << 2, __float_as_int(part)));
;           part += __int_as_float(__builtin_amdgcn_ds_bpermute((lane ^ 32) << 2, __float_as_int(part)));
;           if (fq == 0) reinterpret_cast<float*>(g_lds)[row * 4 + wc] = part;
.LBB0_690:
	global_load_dwordx4 v[126:129], v[148:149], off offset:64
	s_waitcnt vmcnt(0)
	s_and_b64 vcc, exec, s[10:11]
	s_cbranch_vccz .LBB0_662
	s_branch .LBB0_663
.LBB0_691:
	v_mov_b64_e32 v[124:125], v[196:197]
	v_lshlrev_b32_e32 v122, 16, v124
	v_and_b32_e32 v123, 0xffff0000, v124
	v_lshlrev_b32_e32 v124, 16, v125
	v_and_b32_e32 v125, 0xffff0000, v125
	s_cbranch_execnz .LBB0_665
.LBB0_692:
	global_load_dwordx4 v[122:125], v[148:149], off offset:512
	s_waitcnt vmcnt(0)
	s_and_b64 vcc, exec, s[10:11]
	s_cbranch_vccz .LBB0_666
	s_branch .LBB0_667
.LBB0_693:
	v_mov_b64_e32 v[116:117], v[200:201]
	v_lshlrev_b32_e32 v114, 16, v116
	s_waitcnt lgkmcnt(0)
	v_and_b32_e32 v115, 0xffff0000, v116
	v_lshlrev_b32_e32 v116, 16, v117
	v_and_b32_e32 v117, 0xffff0000, v117
	v_lshlrev_b64 v[124:125], 12, v[118:119]
	v_lshl_add_u64 v[124:125], v[136:137], 0, v[124:125]
	s_cbranch_execnz .LBB0_677
.LBB0_694:
	s_waitcnt lgkmcnt(0)
	global_load_dwordx4 v[114:117], v[124:125], off
	s_waitcnt vmcnt(0)
	s_and_b64 vcc, exec, s[10:11]
	v_lshl_add_u64 v[120:121], v[142:143], 0, v[120:121]
	s_cbranch_vccz .LBB0_678
.LBB0_695:
	v_mov_b32_e32 v114, 0
	s_and_b64 vcc, exec, s[8:9]
	s_mov_b64 s[64:65], -1
	s_cbranch_vccz .LBB0_679
	s_branch .LBB0_680
.LBB0_696:
	global_load_dwordx4 v[110:113], v[124:125], off offset:64
	s_waitcnt vmcnt(0)
	s_and_b64 vcc, exec, s[10:11]
	s_cbranch_vccz .LBB0_682
	s_branch .LBB0_683
.LBB0_697:
	v_mov_b64_e32 v[108:109], v[204:205]
	v_lshlrev_b32_e32 v106, 16, v108
	v_and_b32_e32 v107, 0xffff0000, v108
	v_lshlrev_b32_e32 v108, 16, v109
	v_and_b32_e32 v109, 0xffff0000, v109
	s_cbranch_execnz .LBB0_685
.LBB0_698:
	global_load_dwordx4 v[106:109], v[124:125], off offset:512
	s_waitcnt vmcnt(0)
	s_and_b64 vcc, exec, s[10:11]
	s_cbranch_vccz .LBB0_686
	s_branch .LBB0_687
.LBB0_699:
	v_mov_b64_e32 v[104:105], v[206:207]
	v_lshlrev_b32_e32 v102, 16, v104
	v_and_b32_e32 v103, 0xffff0000, v104
	v_lshlrev_b32_e32 v104, 16, v105
	v_and_b32_e32 v105, 0xffff0000, v105
	s_cbranch_execnz .LBB0_689
.LBB0_700:
	global_load_dwordx4 v[102:105], v[124:125], off offset:576
	s_waitcnt vmcnt(0)
	s_and_b64 vcc, exec, s[10:11]
	s_cbranch_vccnz .LBB0_704
.LBB0_701:
	v_pk_add_f32 v[102:103], v[98:99], v[102:103]
	v_pk_add_f32 v[100:101], v[100:101], v[104:105]
	v_mul_f32_e32 v98, v103, v103
	v_fmac_f32_e32 v98, v102, v102
	v_fmac_f32_e32 v98, v100, v100
	v_fmac_f32_e32 v98, v101, v101
	v_add_f32_e32 v98, v114, v98
	ds_bpermute_b32 v99, v126, v98
	v_cvt_pk_bf16_f32 v102, v102, v103
	v_cvt_pk_bf16_f32 v103, v100, v101
	global_store_dwordx2 v[120:121], v[102:103], off offset:288
	s_waitcnt lgkmcnt(0)
	v_add_f32_e32 v98, v98, v99
	ds_bpermute_b32 v99, v0, v98
	s_and_saveexec_b64 s[64:65], s[12:13]
	s_cbranch_execz .LBB0_703
	s_waitcnt lgkmcnt(0)
	v_add_f32_e32 v98, v98, v99
	v_lshl_add_u32 v99, v118, 4, s58
	ds_write_b32 v99, v98

; template <int MODE, bool PRE = false, bool NEXT = false> ...
;     ...
;         float* orow = (float*)e.out + (long)row * e.ldo + cbase;
;         const float* arow = (const float*)e.aux + (long)row * e.ldaux + cbase;
;         const u16* brow = (const u16*)e.aux + (long)row * e.ldaux + cbase;
;         u16* xrow = e.xb + (long)row * 1024 + cbase;
;         float part = 0.f;
.LBB0_704:
	v_or_b32_e32 v102, 32, v138
	v_ashrrev_i32_e32 v103, 31, v102
	v_lshlrev_b64 v[104:105], 11, v[102:103]
	v_lshl_add_u64 v[106:107], v[140:141], 0, v[104:105]
	s_and_b64 vcc, exec, s[8:9]
	s_mov_b64 s[64:65], -1
	s_cbranch_vccz .LBB0_719
	v_lshlrev_b64 v[108:109], 12, v[102:103]
	s_andn2_b64 vcc, exec, s[64:65]
	v_lshl_add_u64 v[108:109], v[136:137], 0, v[108:109]
	s_cbranch_vccz .LBB0_720

; __device__ __forceinline__ float bflo(unsigned w) { return __uint_as_float(w << 16); }
; __device__ __forceinline__ float bfhi(unsigned w) { return __uint_as_float(w & 0xffff0000u); }
; template <int MODE, bool PRE = false, bool NEXT = false> ...
;     ...
;             if (e.auxbf) { const u32x2 w = *reinterpret_cast<const u32x2*>(brow + bj * 128 + n * 16); a = f32x4{bflo(w[0]), bfhi(w[0]), bflo(w[1]), bfhi(w[1])}; }
;             else a = *reinterpret_cast<const f32x4*>(arow + bj * 128 + n * 16);
;             a += acc[ai][bj][m][n];
;             if (e.out) *reinterpret_cast<f32x4*>(orow + bj * 128 + n * 16) = a;
;             if (e.xb) {
;               u32x2 w = {cvtpk(a[0], a[1]), cvtpk(a[2], a[3])};
;               *reinterpret_cast<u32x2*>(xrow + bj * 128 + n * 16) = w;
;               part += a[0] * a[0] + a[1] * a[1] + a[2] * a[2] + a[3] * a[3];
.LBB0_707:
	s_waitcnt lgkmcnt(0)
	v_pk_add_f32 v[94:95], v[94:95], v[98:99]
	v_pk_add_f32 v[96:97], v[96:97], v[100:101]
	v_cvt_pk_bf16_f32 v98, v94, v95
	v_pk_mul_f32 v[94:95], v[94:95], v[94:95]
	v_cvt_pk_bf16_f32 v99, v96, v97
	v_pk_mul_f32 v[96:97], v[96:97], v[96:97]
	v_add_f32_e32 v94, v94, v95
	v_add_f32_e32 v94, v96, v94
	global_store_dwordx2 v[104:105], v[98:99], off
	v_add_f32_e32 v98, v97, v94
	s_and_b64 vcc, exec, s[8:9]
	s_mov_b64 s[64:65], -1
	s_cbranch_vccnz .LBB0_709
.LBB0_708:
	v_mov_b64_e32 v[96:97], v[210:211]
	s_mov_b64 s[64:65], 0
	v_lshlrev_b32_e32 v94, 16, v96
	v_and_b32_e32 v95, 0xffff0000, v96
	v_lshlrev_b32_e32 v96, 16, v97
	v_and_b32_e32 v97, 0xffff0000, v97

; template <int MODE, bool PRE = false, bool NEXT = false> ...
;     ...
;             a += acc[ai][bj][m][n];
;             if (e.out) *reinterpret_cast<f32x4*>(orow + bj * 128 + n * 16) = a;
;             if (e.xb) {
;               u32x2 w = {cvtpk(a[0], a[1]), cvtpk(a[2], a[3])};
;               *reinterpret_cast<u32x2*>(xrow + bj * 128 + n * 16) = w;
;               part += a[0] * a[0] + a[1] * a[1] + a[2] * a[2] + a[3] * a[3];
.LBB0_711:
	v_pk_add_f32 v[90:91], v[90:91], v[94:95]
	v_pk_add_f32 v[92:93], v[92:93], v[96:97]
	v_cvt_pk_bf16_f32 v94, v90, v91
	v_pk_mul_f32 v[90:91], v[90:91], v[90:91]
	v_cvt_pk_bf16_f32 v95, v92, v93
	v_pk_mul_f32 v[92:93], v[92:93], v[92:93]
	v_add_f32_e32 v90, v90, v91
	v_add_f32_e32 v90, v92, v90
	v_add_f32_e32 v90, v93, v90
	v_add_f32_e32 v98, v98, v90
	global_store_dwordx2 v[104:105], v[94:95], off offset:32

; template <int MODE, bool PRE = false, bool NEXT = false> ...
;     ...
;             a += acc[ai][bj][m][n];
;             if (e.out) *reinterpret_cast<f32x4*>(orow + bj * 128 + n * 16) = a;
;             if (e.xb) {
;               u32x2 w = {cvtpk(a[0], a[1]), cvtpk(a[2], a[3])};
;               *reinterpret_cast<u32x2*>(xrow + bj * 128 + n * 16) = w;
;               part += a[0] * a[0] + a[1] * a[1] + a[2] * a[2] + a[3] * a[3];
.LBB0_715:
	v_pk_add_f32 v[86:87], v[86:87], v[90:91]
	v_pk_add_f32 v[88:89], v[88:89], v[92:93]
	v_cvt_pk_bf16_f32 v90, v86, v87
	v_pk_mul_f32 v[86:87], v[86:87], v[86:87]
	v_cvt_pk_bf16_f32 v91, v88, v89
	v_pk_mul_f32 v[88:89], v[88:89], v[88:89]
	v_add_f32_e32 v86, v86, v87
	v_add_f32_e32 v86, v88, v86
	v_add_f32_e32 v86, v89, v86
	v_add_f32_e32 v98, v98, v86
	global_store_dwordx2 v[104:105], v[90:91], off offset:256

; __device__ __forceinline__ float bflo(unsigned w) { return __uint_as_float(w << 16); }
; __device__ __forceinline__ float bfhi(unsigned w) { return __uint_as_float(w & 0xffff0000u); }
; template <int MODE, bool PRE = false, bool NEXT = false> ...
;     ...
;             if (e.auxbf) { const u32x2 w = *reinterpret_cast<const u32x2*>(brow + bj * 128 + n * 16); a = f32x4{bflo(w[0]), bfhi(w[0]), bflo(w[1]), bfhi(w[1])}; }
;             else a = *reinterpret_cast<const f32x4*>(arow + bj * 128 + n * 16);
;             a += acc[ai][bj][m][n];
;             if (e.out) *reinterpret_cast<f32x4*>(orow + bj * 128 + n * 16) = a;
;             if (e.xb) {
;               u32x2 w = {cvtpk(a[0], a[1]), cvtpk(a[2], a[3])};
;               *reinterpret_cast<u32x2*>(xrow + bj * 128 + n * 16) = w;
;               part += a[0] * a[0] + a[1] * a[1] + a[2] * a[2] + a[3] * a[3];
;             }
;           }
;         if (e.xb) {
;           part += __int_as_float(__builtin_amdgcn_ds_bpermute((lane ^ 16) << 2, __float_as_int(part)));
;           part += __int_as_float(__builtin_amdgcn_ds_bpermute((lane ^ 32) << 2, __float_as_int(part)));
;           if (fq == 0) reinterpret_cast<float*>(g_lds)[row * 4 + wc] = part;
.LBB0_719:
	v_mov_b64_e32 v[100:101], v[208:209]
	v_lshlrev_b32_e32 v98, 16, v100
	s_waitcnt lgkmcnt(0)
	v_and_b32_e32 v99, 0xffff0000, v100
	v_lshlrev_b32_e32 v100, 16, v101
	v_and_b32_e32 v101, 0xffff0000, v101
	v_lshlrev_b64 v[108:109], 12, v[102:103]
	v_lshl_add_u64 v[108:109], v[136:137], 0, v[108:109]
	s_cbranch_execnz .LBB0_706
.LBB0_720:
	s_waitcnt lgkmcnt(0)
	global_load_dwordx4 v[98:101], v[108:109], off
	s_waitcnt vmcnt(0)
	s_and_b64 vcc, exec, s[10:11]
	v_lshl_add_u64 v[104:105], v[142:143], 0, v[104:105]
	s_cbranch_vccz .LBB0_707
.LBB0_721:
	v_mov_b32_e32 v98, 0
	s_and_b64 vcc, exec, s[8:9]
	s_mov_b64 s[64:65], -1
	s_cbranch_vccz .LBB0_708
	s_branch .LBB0_709
.LBB0_722:
	global_load_dwordx4 v[94:97], v[108:109], off offset:64
	s_waitcnt vmcnt(0)
	s_and_b64 vcc, exec, s[10:11]
	s_cbranch_vccz .LBB0_711
	s_branch .LBB0_712
.LBB0_723:
	v_mov_b64_e32 v[92:93], v[212:213]
	v_lshlrev_b32_e32 v90, 16, v92
	v_and_b32_e32 v91, 0xffff0000, v92
	v_lshlrev_b32_e32 v92, 16, v93
	v_and_b32_e32 v93, 0xffff0000, v93
	s_cbranch_execnz .LBB0_714
.LBB0_724:
	global_load_dwordx4 v[90:93], v[108:109], off offset:512
	s_waitcnt vmcnt(0)
	s_and_b64 vcc, exec, s[10:11]
	s_cbranch_vccz .LBB0_715
	s_branch .LBB0_716
.LBB0_725:
	v_mov_b64_e32 v[88:89], v[214:215]
	v_lshlrev_b32_e32 v86, 16, v88
	v_and_b32_e32 v87, 0xffff0000, v88
	v_lshlrev_b32_e32 v88, 16, v89
	v_and_b32_e32 v89, 0xffff0000, v89
	s_cbranch_execnz .LBB0_718
.LBB0_726:
	global_load_dwordx4 v[86:89], v[108:109], off offset:576
	s_waitcnt vmcnt(0)
	s_and_b64 vcc, exec, s[10:11]
	s_cbranch_vccnz .LBB0_730
.LBB0_727:
	v_pk_add_f32 v[86:87], v[82:83], v[86:87]
	v_pk_add_f32 v[84:85], v[84:85], v[88:89]
	v_mul_f32_e32 v82, v87, v87
	v_fmac_f32_e32 v82, v86, v86
	v_fmac_f32_e32 v82, v84, v84
	v_fmac_f32_e32 v82, v85, v85
	v_add_f32_e32 v82, v98, v82
	ds_bpermute_b32 v83, v126, v82
	v_cvt_pk_bf16_f32 v86, v86, v87
	v_cvt_pk_bf16_f32 v87, v84, v85
	global_store_dwordx2 v[104:105], v[86:87], off offset:288
	s_waitcnt lgkmcnt(0)
	v_add_f32_e32 v82, v82, v83
	ds_bpermute_b32 v83, v0, v82
	s_and_saveexec_b64 s[64:65], s[12:13]
	s_cbranch_execz .LBB0_729
	s_waitcnt lgkmcnt(0)
	v_add_f32_e32 v82, v82, v83
	v_lshl_add_u32 v83, v102, 4, s58
	ds_write_b32 v83, v82

; template <int MODE, bool PRE = false, bool NEXT = false> ...
;     ...
;         float* orow = (float*)e.out + (long)row * e.ldo + cbase;
;         const float* arow = (const float*)e.aux + (long)row * e.ldaux + cbase;
;         const u16* brow = (const u16*)e.aux + (long)row * e.ldaux + cbase;
;         u16* xrow = e.xb + (long)row * 1024 + cbase;
;         float part = 0.f;
.LBB0_730:
	v_or_b32_e32 v86, 48, v138
	v_ashrrev_i32_e32 v87, 31, v86
	v_lshlrev_b64 v[88:89], 11, v[86:87]
	v_lshl_add_u64 v[90:91], v[140:141], 0, v[88:89]
	s_and_b64 vcc, exec, s[8:9]
	s_mov_b64 s[64:65], -1
	s_cbranch_vccz .LBB0_745
	v_lshlrev_b64 v[92:93], 12, v[86:87]
	s_andn2_b64 vcc, exec, s[64:65]
	v_lshl_add_u64 v[92:93], v[136:137], 0, v[92:93]
	s_cbranch_vccz .LBB0_746

; __device__ __forceinline__ float bflo(unsigned w) { return __uint_as_float(w << 16); }
; __device__ __forceinline__ float bfhi(unsigned w) { return __uint_as_float(w & 0xffff0000u); }
; template <int MODE, bool PRE = false, bool NEXT = false> ...
;     ...
;             if (e.auxbf) { const u32x2 w = *reinterpret_cast<const u32x2*>(brow + bj * 128 + n * 16); a = f32x4{bflo(w[0]), bfhi(w[0]), bflo(w[1]), bfhi(w[1])}; }
;             else a = *reinterpret_cast<const f32x4*>(arow + bj * 128 + n * 16);
;             a += acc[ai][bj][m][n];
;             if (e.out) *reinterpret_cast<f32x4*>(orow + bj * 128 + n * 16) = a;
;             if (e.xb) {
;               u32x2 w = {cvtpk(a[0], a[1]), cvtpk(a[2], a[3])};
;               *reinterpret_cast<u32x2*>(xrow + bj * 128 + n * 16) = w;
;               part += a[0] * a[0] + a[1] * a[1] + a[2] * a[2] + a[3] * a[3];
.LBB0_733:
	s_waitcnt lgkmcnt(0)
	v_pk_add_f32 v[78:79], v[78:79], v[82:83]
	v_pk_add_f32 v[80:81], v[80:81], v[84:85]
	v_cvt_pk_bf16_f32 v82, v78, v79
	v_pk_mul_f32 v[78:79], v[78:79], v[78:79]
	v_cvt_pk_bf16_f32 v83, v80, v81
	v_pk_mul_f32 v[80:81], v[80:81], v[80:81]
	v_add_f32_e32 v78, v78, v79
	v_add_f32_e32 v78, v80, v78
	global_store_dwordx2 v[88:89], v[82:83], off
	v_add_f32_e32 v82, v81, v78
	s_and_b64 vcc, exec, s[8:9]
	s_mov_b64 s[64:65], -1
	s_cbranch_vccnz .LBB0_735
.LBB0_734:
	v_mov_b64_e32 v[80:81], v[218:219]
	s_mov_b64 s[64:65], 0
	v_lshlrev_b32_e32 v78, 16, v80
	v_and_b32_e32 v79, 0xffff0000, v80
	v_lshlrev_b32_e32 v80, 16, v81
	v_and_b32_e32 v81, 0xffff0000, v81

; template <int MODE, bool PRE = false, bool NEXT = false> ...
;     ...
;             a += acc[ai][bj][m][n];
;             if (e.out) *reinterpret_cast<f32x4*>(orow + bj * 128 + n * 16) = a;
;             if (e.xb) {
;               u32x2 w = {cvtpk(a[0], a[1]), cvtpk(a[2], a[3])};
;               *reinterpret_cast<u32x2*>(xrow + bj * 128 + n * 16) = w;
;               part += a[0] * a[0] + a[1] * a[1] + a[2] * a[2] + a[3] * a[3];
.LBB0_737:
	v_pk_add_f32 v[74:75], v[74:75], v[78:79]
	v_pk_add_f32 v[76:77], v[76:77], v[80:81]
	v_cvt_pk_bf16_f32 v78, v74, v75
	v_pk_mul_f32 v[74:75], v[74:75], v[74:75]
	v_cvt_pk_bf16_f32 v79, v76, v77
	v_pk_mul_f32 v[76:77], v[76:77], v[76:77]
	v_add_f32_e32 v74, v74, v75
	v_add_f32_e32 v74, v76, v74
	v_add_f32_e32 v74, v77, v74
	v_add_f32_e32 v82, v82, v74
	global_store_dwordx2 v[88:89], v[78:79], off offset:32

; template <int MODE, bool PRE = false, bool NEXT = false> ...
;     ...
;             a += acc[ai][bj][m][n];
;             if (e.out) *reinterpret_cast<f32x4*>(orow + bj * 128 + n * 16) = a;
;             if (e.xb) {
;               u32x2 w = {cvtpk(a[0], a[1]), cvtpk(a[2], a[3])};
;               *reinterpret_cast<u32x2*>(xrow + bj * 128 + n * 16) = w;
;               part += a[0] * a[0] + a[1] * a[1] + a[2] * a[2] + a[3] * a[3];
.LBB0_741:
	v_pk_add_f32 v[70:71], v[70:71], v[74:75]
	v_pk_add_f32 v[72:73], v[72:73], v[76:77]
	v_cvt_pk_bf16_f32 v74, v70, v71
	v_pk_mul_f32 v[70:71], v[70:71], v[70:71]
	v_cvt_pk_bf16_f32 v75, v72, v73
	v_pk_mul_f32 v[72:73], v[72:73], v[72:73]
	v_add_f32_e32 v70, v70, v71
	v_add_f32_e32 v70, v72, v70
	v_add_f32_e32 v70, v73, v70
	v_add_f32_e32 v82, v82, v70
	global_store_dwordx2 v[88:89], v[74:75], off offset:256

; __device__ __forceinline__ float bflo(unsigned w) { return __uint_as_float(w << 16); }
; __device__ __forceinline__ float bfhi(unsigned w) { return __uint_as_float(w & 0xffff0000u); }
; template <int MODE, bool PRE = false, bool NEXT = false> ...
;     ...
;             if (e.auxbf) { const u32x2 w = *reinterpret_cast<const u32x2*>(brow + bj * 128 + n * 16); a = f32x4{bflo(w[0]), bfhi(w[0]), bflo(w[1]), bfhi(w[1])}; }
;             else a = *reinterpret_cast<const f32x4*>(arow + bj * 128 + n * 16);
;             a += acc[ai][bj][m][n];
;             if (e.out) *reinterpret_cast<f32x4*>(orow + bj * 128 + n * 16) = a;
;             if (e.xb) {
;               u32x2 w = {cvtpk(a[0], a[1]), cvtpk(a[2], a[3])};
;               *reinterpret_cast<u32x2*>(xrow + bj * 128 + n * 16) = w;
;               part += a[0] * a[0] + a[1] * a[1] + a[2] * a[2] + a[3] * a[3];
;             }
;           }
;         if (e.xb) {
;           part += __int_as_float(__builtin_amdgcn_ds_bpermute((lane ^ 16) << 2, __float_as_int(part)));
;           part += __int_as_float(__builtin_amdgcn_ds_bpermute((lane ^ 32) << 2, __float_as_int(part)));
;           if (fq == 0) reinterpret_cast<float*>(g_lds)[row * 4 + wc] = part;
.LBB0_745:
	v_mov_b64_e32 v[84:85], v[216:217]
	v_lshlrev_b32_e32 v82, 16, v84
	s_waitcnt lgkmcnt(0)
	v_and_b32_e32 v83, 0xffff0000, v84
	v_lshlrev_b32_e32 v84, 16, v85
	v_and_b32_e32 v85, 0xffff0000, v85
	v_lshlrev_b64 v[92:93], 12, v[86:87]
	v_lshl_add_u64 v[92:93], v[136:137], 0, v[92:93]
	s_cbranch_execnz .LBB0_732
.LBB0_746:
	s_waitcnt lgkmcnt(0)
	global_load_dwordx4 v[82:85], v[92:93], off
	s_waitcnt vmcnt(0)
	s_and_b64 vcc, exec, s[10:11]
	v_lshl_add_u64 v[88:89], v[142:143], 0, v[88:89]
	s_cbranch_vccz .LBB0_733
.LBB0_747:
	v_mov_b32_e32 v82, 0
	s_and_b64 vcc, exec, s[8:9]
	s_mov_b64 s[64:65], -1
	s_cbranch_vccz .LBB0_734
	s_branch .LBB0_735
.LBB0_748:
	global_load_dwordx4 v[78:81], v[92:93], off offset:64
	s_waitcnt vmcnt(0)
	s_and_b64 vcc, exec, s[10:11]
	s_cbranch_vccz .LBB0_737
	s_branch .LBB0_738
.LBB0_749:
	v_mov_b64_e32 v[76:77], v[220:221]
	v_lshlrev_b32_e32 v74, 16, v76
	v_and_b32_e32 v75, 0xffff0000, v76
	v_lshlrev_b32_e32 v76, 16, v77
	v_and_b32_e32 v77, 0xffff0000, v77
	s_cbranch_execnz .LBB0_740
.LBB0_750:
	global_load_dwordx4 v[74:77], v[92:93], off offset:512
	s_waitcnt vmcnt(0)
	s_and_b64 vcc, exec, s[10:11]
	s_cbranch_vccz .LBB0_741
	s_branch .LBB0_742
.LBB0_751:
	v_mov_b64_e32 v[72:73], v[222:223]
	v_lshlrev_b32_e32 v70, 16, v72
	v_and_b32_e32 v71, 0xffff0000, v72
	v_lshlrev_b32_e32 v72, 16, v73
	v_and_b32_e32 v73, 0xffff0000, v73
	s_cbranch_execnz .LBB0_744
.LBB0_752:
	global_load_dwordx4 v[70:73], v[92:93], off offset:576
	s_waitcnt vmcnt(0)
	s_and_b64 vcc, exec, s[10:11]
	s_cbranch_vccnz .LBB0_756
.LBB0_753:
	v_pk_add_f32 v[70:71], v[66:67], v[70:71]
	v_pk_add_f32 v[68:69], v[68:69], v[72:73]
	v_mul_f32_e32 v66, v71, v71
	v_fmac_f32_e32 v66, v70, v70
	v_fmac_f32_e32 v66, v68, v68
	v_fmac_f32_e32 v66, v69, v69
	v_add_f32_e32 v66, v82, v66
	ds_bpermute_b32 v67, v126, v66
	v_cvt_pk_bf16_f32 v70, v70, v71
	v_cvt_pk_bf16_f32 v71, v68, v69
	global_store_dwordx2 v[88:89], v[70:71], off offset:288
	s_waitcnt lgkmcnt(0)
	v_add_f32_e32 v66, v66, v67
	ds_bpermute_b32 v67, v0, v66
	s_and_saveexec_b64 s[64:65], s[12:13]
	s_cbranch_execz .LBB0_755
	s_waitcnt lgkmcnt(0)
	v_add_f32_e32 v66, v66, v67
	v_lshl_add_u32 v67, v86, 4, s58
	ds_write_b32 v67, v66

; template <int MODE, bool PRE = false, bool NEXT = false> ...
;     ...
;         float* orow = (float*)e.out + (long)row * e.ldo + cbase;
;         const float* arow = (const float*)e.aux + (long)row * e.ldaux + cbase;
;         const u16* brow = (const u16*)e.aux + (long)row * e.ldaux + cbase;
;         u16* xrow = e.xb + (long)row * 1024 + cbase;
;         float part = 0.f;
.LBB0_756:
	v_add_u32_e32 v70, 0x80, v138
	v_ashrrev_i32_e32 v71, 31, v70
	v_lshlrev_b64 v[72:73], 11, v[70:71]
	v_lshl_add_u64 v[74:75], v[140:141], 0, v[72:73]
	s_and_b64 vcc, exec, s[8:9]
	s_mov_b64 s[64:65], -1
	s_cbranch_vccz .LBB0_771
	v_lshlrev_b64 v[76:77], 12, v[70:71]
	s_andn2_b64 vcc, exec, s[64:65]
	v_lshl_add_u64 v[76:77], v[136:137], 0, v[76:77]
	s_cbranch_vccz .LBB0_772

; __device__ __forceinline__ float bflo(unsigned w) { return __uint_as_float(w << 16); }
; __device__ __forceinline__ float bfhi(unsigned w) { return __uint_as_float(w & 0xffff0000u); }
; template <int MODE, bool PRE = false, bool NEXT = false> ...
;     ...
;             if (e.auxbf) { const u32x2 w = *reinterpret_cast<const u32x2*>(brow + bj * 128 + n * 16); a = f32x4{bflo(w[0]), bfhi(w[0]), bflo(w[1]), bfhi(w[1])}; }
;             else a = *reinterpret_cast<const f32x4*>(arow + bj * 128 + n * 16);
;             a += acc[ai][bj][m][n];
;             if (e.out) *reinterpret_cast<f32x4*>(orow + bj * 128 + n * 16) = a;
;             if (e.xb) {
;               u32x2 w = {cvtpk(a[0], a[1]), cvtpk(a[2], a[3])};
;               *reinterpret_cast<u32x2*>(xrow + bj * 128 + n * 16) = w;
;               part += a[0] * a[0] + a[1] * a[1] + a[2] * a[2] + a[3] * a[3];
.LBB0_759:
	s_waitcnt lgkmcnt(0)
	v_pk_add_f32 v[62:63], v[62:63], v[66:67]
	v_pk_add_f32 v[64:65], v[64:65], v[68:69]
	v_cvt_pk_bf16_f32 v66, v62, v63
	v_pk_mul_f32 v[62:63], v[62:63], v[62:63]
	v_cvt_pk_bf16_f32 v67, v64, v65
	v_pk_mul_f32 v[64:65], v[64:65], v[64:65]
	v_add_f32_e32 v62, v62, v63
	v_add_f32_e32 v62, v64, v62
	global_store_dwordx2 v[72:73], v[66:67], off
	v_add_f32_e32 v66, v65, v62
	s_and_b64 vcc, exec, s[8:9]
	s_mov_b64 s[64:65], -1
	s_cbranch_vccnz .LBB0_761
.LBB0_760:
	v_mov_b64_e32 v[64:65], v[226:227]
	s_mov_b64 s[64:65], 0
	v_lshlrev_b32_e32 v62, 16, v64
	v_and_b32_e32 v63, 0xffff0000, v64
	v_lshlrev_b32_e32 v64, 16, v65
	v_and_b32_e32 v65, 0xffff0000, v65

; template <int MODE, bool PRE = false, bool NEXT = false> ...
;     ...
;             a += acc[ai][bj][m][n];
;             if (e.out) *reinterpret_cast<f32x4*>(orow + bj * 128 + n * 16) = a;
;             if (e.xb) {
;               u32x2 w = {cvtpk(a[0], a[1]), cvtpk(a[2], a[3])};
;               *reinterpret_cast<u32x2*>(xrow + bj * 128 + n * 16) = w;
;               part += a[0] * a[0] + a[1] * a[1] + a[2] * a[2] + a[3] * a[3];
.LBB0_763:
	v_pk_add_f32 v[58:59], v[58:59], v[62:63]
	v_pk_add_f32 v[60:61], v[60:61], v[64:65]
	v_cvt_pk_bf16_f32 v62, v58, v59
	v_pk_mul_f32 v[58:59], v[58:59], v[58:59]
	v_cvt_pk_bf16_f32 v63, v60, v61
	v_pk_mul_f32 v[60:61], v[60:61], v[60:61]
	v_add_f32_e32 v58, v58, v59
	v_add_f32_e32 v58, v60, v58
	v_add_f32_e32 v58, v61, v58
	v_add_f32_e32 v66, v66, v58
	global_store_dwordx2 v[72:73], v[62:63], off offset:32

; template <int MODE, bool PRE = false, bool NEXT = false> ...
;     ...
;             a += acc[ai][bj][m][n];
;             if (e.out) *reinterpret_cast<f32x4*>(orow + bj * 128 + n * 16) = a;
;             if (e.xb) {
;               u32x2 w = {cvtpk(a[0], a[1]), cvtpk(a[2], a[3])};
;               *reinterpret_cast<u32x2*>(xrow + bj * 128 + n * 16) = w;
;               part += a[0] * a[0] + a[1] * a[1] + a[2] * a[2] + a[3] * a[3];
.LBB0_767:
	v_pk_add_f32 v[54:55], v[54:55], v[58:59]
	v_pk_add_f32 v[56:57], v[56:57], v[60:61]
	v_cvt_pk_bf16_f32 v58, v54, v55
	v_pk_mul_f32 v[54:55], v[54:55], v[54:55]
	v_cvt_pk_bf16_f32 v59, v56, v57
	v_pk_mul_f32 v[56:57], v[56:57], v[56:57]
	v_add_f32_e32 v54, v54, v55
	v_add_f32_e32 v54, v56, v54
	v_add_f32_e32 v54, v57, v54
	v_add_f32_e32 v66, v66, v54
	global_store_dwordx2 v[72:73], v[58:59], off offset:256

; __device__ __forceinline__ float bflo(unsigned w) { return __uint_as_float(w << 16); }
; __device__ __forceinline__ float bfhi(unsigned w) { return __uint_as_float(w & 0xffff0000u); }
; template <int MODE, bool PRE = false, bool NEXT = false> ...
;     ...
;             if (e.auxbf) { const u32x2 w = *reinterpret_cast<const u32x2*>(brow + bj * 128 + n * 16); a = f32x4{bflo(w[0]), bfhi(w[0]), bflo(w[1]), bfhi(w[1])}; }
;             else a = *reinterpret_cast<const f32x4*>(arow + bj * 128 + n * 16);
;             a += acc[ai][bj][m][n];
;             if (e.out) *reinterpret_cast<f32x4*>(orow + bj * 128 + n * 16) = a;
;             if (e.xb) {
;               u32x2 w = {cvtpk(a[0], a[1]), cvtpk(a[2], a[3])};
;               *reinterpret_cast<u32x2*>(xrow + bj * 128 + n * 16) = w;
;               part += a[0] * a[0] + a[1] * a[1] + a[2] * a[2] + a[3] * a[3];
;             }
;           }
;         if (e.xb) {
;           part += __int_as_float(__builtin_amdgcn_ds_bpermute((lane ^ 16) << 2, __float_as_int(part)));
;           part += __int_as_float(__builtin_amdgcn_ds_bpermute((lane ^ 32) << 2, __float_as_int(part)));
;           if (fq == 0) reinterpret_cast<float*>(g_lds)[row * 4 + wc] = part;
.LBB0_771:
	v_mov_b64_e32 v[68:69], v[224:225]
	v_lshlrev_b32_e32 v66, 16, v68
	s_waitcnt lgkmcnt(0)
	v_and_b32_e32 v67, 0xffff0000, v68
	v_lshlrev_b32_e32 v68, 16, v69
	v_and_b32_e32 v69, 0xffff0000, v69
	v_lshlrev_b64 v[76:77], 12, v[70:71]
	v_lshl_add_u64 v[76:77], v[136:137], 0, v[76:77]
	s_cbranch_execnz .LBB0_758
.LBB0_772:
	s_waitcnt lgkmcnt(0)
	global_load_dwordx4 v[66:69], v[76:77], off
	s_waitcnt vmcnt(0)
	s_and_b64 vcc, exec, s[10:11]
	v_lshl_add_u64 v[72:73], v[142:143], 0, v[72:73]
	s_cbranch_vccz .LBB0_759
.LBB0_773:
	v_mov_b32_e32 v66, 0
	s_and_b64 vcc, exec, s[8:9]
	s_mov_b64 s[64:65], -1
	s_cbranch_vccz .LBB0_760
	s_branch .LBB0_761
.LBB0_774:
	global_load_dwordx4 v[62:65], v[76:77], off offset:64
	s_waitcnt vmcnt(0)
	s_and_b64 vcc, exec, s[10:11]
	s_cbranch_vccz .LBB0_763
	s_branch .LBB0_764
.LBB0_775:
	v_mov_b64_e32 v[60:61], v[228:229]
	v_lshlrev_b32_e32 v58, 16, v60
	v_and_b32_e32 v59, 0xffff0000, v60
	v_lshlrev_b32_e32 v60, 16, v61
	v_and_b32_e32 v61, 0xffff0000, v61
	s_cbranch_execnz .LBB0_766
.LBB0_776:
	global_load_dwordx4 v[58:61], v[76:77], off offset:512
	s_waitcnt vmcnt(0)
	s_and_b64 vcc, exec, s[10:11]
	s_cbranch_vccz .LBB0_767
	s_branch .LBB0_768
.LBB0_777:
	v_mov_b64_e32 v[56:57], v[230:231]
	v_lshlrev_b32_e32 v54, 16, v56
	v_and_b32_e32 v55, 0xffff0000, v56
	v_lshlrev_b32_e32 v56, 16, v57
	v_and_b32_e32 v57, 0xffff0000, v57
	s_cbranch_execnz .LBB0_770
.LBB0_778:
	global_load_dwordx4 v[54:57], v[76:77], off offset:576
	s_waitcnt vmcnt(0)
	s_and_b64 vcc, exec, s[10:11]
	s_cbranch_vccnz .LBB0_782
.LBB0_779:
	v_pk_add_f32 v[54:55], v[50:51], v[54:55]
	v_pk_add_f32 v[52:53], v[52:53], v[56:57]
	v_mul_f32_e32 v50, v55, v55
	v_fmac_f32_e32 v50, v54, v54
	v_fmac_f32_e32 v50, v52, v52
	v_fmac_f32_e32 v50, v53, v53
	v_add_f32_e32 v50, v66, v50
	ds_bpermute_b32 v51, v126, v50
	v_cvt_pk_bf16_f32 v54, v54, v55
	v_cvt_pk_bf16_f32 v55, v52, v53
	global_store_dwordx2 v[72:73], v[54:55], off offset:288
	s_waitcnt lgkmcnt(0)
	v_add_f32_e32 v50, v50, v51
	ds_bpermute_b32 v51, v0, v50
	s_and_saveexec_b64 s[64:65], s[12:13]
	s_cbranch_execz .LBB0_781
	s_waitcnt lgkmcnt(0)
	v_add_f32_e32 v50, v50, v51
	v_lshl_add_u32 v51, v70, 4, s58
	ds_write_b32 v51, v50

; template <int MODE, bool PRE = false, bool NEXT = false> ...
;     ...
;         float* orow = (float*)e.out + (long)row * e.ldo + cbase;
;         const float* arow = (const float*)e.aux + (long)row * e.ldaux + cbase;
;         const u16* brow = (const u16*)e.aux + (long)row * e.ldaux + cbase;
;         u16* xrow = e.xb + (long)row * 1024 + cbase;
;         float part = 0.f;
.LBB0_782:
	v_add_u32_e32 v54, 0x90, v138
	v_ashrrev_i32_e32 v55, 31, v54
	v_lshlrev_b64 v[56:57], 11, v[54:55]
	v_lshl_add_u64 v[58:59], v[140:141], 0, v[56:57]
	s_and_b64 vcc, exec, s[8:9]
	s_mov_b64 s[64:65], -1
	s_cbranch_vccz .LBB0_797
	v_lshlrev_b64 v[60:61], 12, v[54:55]
	s_andn2_b64 vcc, exec, s[64:65]
	v_lshl_add_u64 v[60:61], v[136:137], 0, v[60:61]
	s_cbranch_vccz .LBB0_798

; __device__ __forceinline__ float bflo(unsigned w) { return __uint_as_float(w << 16); }
; __device__ __forceinline__ float bfhi(unsigned w) { return __uint_as_float(w & 0xffff0000u); }
; template <int MODE, bool PRE = false, bool NEXT = false> ...
;     ...
;             if (e.auxbf) { const u32x2 w = *reinterpret_cast<const u32x2*>(brow + bj * 128 + n * 16); a = f32x4{bflo(w[0]), bfhi(w[0]), bflo(w[1]), bfhi(w[1])}; }
;             else a = *reinterpret_cast<const f32x4*>(arow + bj * 128 + n * 16);
;             a += acc[ai][bj][m][n];
;             if (e.out) *reinterpret_cast<f32x4*>(orow + bj * 128 + n * 16) = a;
;             if (e.xb) {
;               u32x2 w = {cvtpk(a[0], a[1]), cvtpk(a[2], a[3])};
;               *reinterpret_cast<u32x2*>(xrow + bj * 128 + n * 16) = w;
;               part += a[0] * a[0] + a[1] * a[1] + a[2] * a[2] + a[3] * a[3];
.LBB0_785:
	s_waitcnt lgkmcnt(0)
	v_pk_add_f32 v[46:47], v[46:47], v[50:51]
	v_pk_add_f32 v[48:49], v[48:49], v[52:53]
	v_cvt_pk_bf16_f32 v50, v46, v47
	v_pk_mul_f32 v[46:47], v[46:47], v[46:47]
	v_cvt_pk_bf16_f32 v51, v48, v49
	v_pk_mul_f32 v[48:49], v[48:49], v[48:49]
	v_add_f32_e32 v46, v46, v47
	v_add_f32_e32 v46, v48, v46
	global_store_dwordx2 v[56:57], v[50:51], off
	v_add_f32_e32 v50, v49, v46
	s_and_b64 vcc, exec, s[8:9]
	s_mov_b64 s[64:65], -1
	s_cbranch_vccnz .LBB0_787
.LBB0_786:
	v_mov_b64_e32 v[48:49], v[234:235]
	s_mov_b64 s[64:65], 0
	v_lshlrev_b32_e32 v46, 16, v48
	v_and_b32_e32 v47, 0xffff0000, v48
	v_lshlrev_b32_e32 v48, 16, v49
	v_and_b32_e32 v49, 0xffff0000, v49

; template <int MODE, bool PRE = false, bool NEXT = false> ...
;     ...
;             a += acc[ai][bj][m][n];
;             if (e.out) *reinterpret_cast<f32x4*>(orow + bj * 128 + n * 16) = a;
;             if (e.xb) {
;               u32x2 w = {cvtpk(a[0], a[1]), cvtpk(a[2], a[3])};
;               *reinterpret_cast<u32x2*>(xrow + bj * 128 + n * 16) = w;
;               part += a[0] * a[0] + a[1] * a[1] + a[2] * a[2] + a[3] * a[3];
.LBB0_789:
	v_pk_add_f32 v[42:43], v[42:43], v[46:47]
	v_pk_add_f32 v[44:45], v[44:45], v[48:49]
	v_cvt_pk_bf16_f32 v46, v42, v43
	v_pk_mul_f32 v[42:43], v[42:43], v[42:43]
	v_cvt_pk_bf16_f32 v47, v44, v45
	v_pk_mul_f32 v[44:45], v[44:45], v[44:45]
	v_add_f32_e32 v42, v42, v43
	v_add_f32_e32 v42, v44, v42
	v_add_f32_e32 v42, v45, v42
	v_add_f32_e32 v50, v50, v42
	global_store_dwordx2 v[56:57], v[46:47], off offset:32

; template <int MODE, bool PRE = false, bool NEXT = false> ...
;     ...
;             a += acc[ai][bj][m][n];
;             if (e.out) *reinterpret_cast<f32x4*>(orow + bj * 128 + n * 16) = a;
;             if (e.xb) {
;               u32x2 w = {cvtpk(a[0], a[1]), cvtpk(a[2], a[3])};
;               *reinterpret_cast<u32x2*>(xrow + bj * 128 + n * 16) = w;
;               part += a[0] * a[0] + a[1] * a[1] + a[2] * a[2] + a[3] * a[3];
.LBB0_793:
	v_pk_add_f32 v[38:39], v[38:39], v[42:43]
	v_pk_add_f32 v[40:41], v[40:41], v[44:45]
	v_cvt_pk_bf16_f32 v42, v38, v39
	v_pk_mul_f32 v[38:39], v[38:39], v[38:39]
	v_cvt_pk_bf16_f32 v43, v40, v41
	v_pk_mul_f32 v[40:41], v[40:41], v[40:41]
	v_add_f32_e32 v38, v38, v39
	v_add_f32_e32 v38, v40, v38
	v_add_f32_e32 v38, v41, v38
	v_add_f32_e32 v50, v50, v38
	global_store_dwordx2 v[56:57], v[42:43], off offset:256

; __device__ __forceinline__ float bflo(unsigned w) { return __uint_as_float(w << 16); }
; __device__ __forceinline__ float bfhi(unsigned w) { return __uint_as_float(w & 0xffff0000u); }
; template <int MODE, bool PRE = false, bool NEXT = false> ...
;     ...
;             if (e.auxbf) { const u32x2 w = *reinterpret_cast<const u32x2*>(brow + bj * 128 + n * 16); a = f32x4{bflo(w[0]), bfhi(w[0]), bflo(w[1]), bfhi(w[1])}; }
;             else a = *reinterpret_cast<const f32x4*>(arow + bj * 128 + n * 16);
;             a += acc[ai][bj][m][n];
;             if (e.out) *reinterpret_cast<f32x4*>(orow + bj * 128 + n * 16) = a;
;             if (e.xb) {
;               u32x2 w = {cvtpk(a[0], a[1]), cvtpk(a[2], a[3])};
;               *reinterpret_cast<u32x2*>(xrow + bj * 128 + n * 16) = w;
;               part += a[0] * a[0] + a[1] * a[1] + a[2] * a[2] + a[3] * a[3];
;             }
;           }
;         if (e.xb) {
;           part += __int_as_float(__builtin_amdgcn_ds_bpermute((lane ^ 16) << 2, __float_as_int(part)));
;           part += __int_as_float(__builtin_amdgcn_ds_bpermute((lane ^ 32) << 2, __float_as_int(part)));
;           if (fq == 0) reinterpret_cast<float*>(g_lds)[row * 4 + wc] = part;
.LBB0_797:
	v_mov_b64_e32 v[52:53], v[232:233]
	v_lshlrev_b32_e32 v50, 16, v52
	s_waitcnt lgkmcnt(0)
	v_and_b32_e32 v51, 0xffff0000, v52
	v_lshlrev_b32_e32 v52, 16, v53
	v_and_b32_e32 v53, 0xffff0000, v53
	v_lshlrev_b64 v[60:61], 12, v[54:55]
	v_lshl_add_u64 v[60:61], v[136:137], 0, v[60:61]
	s_cbranch_execnz .LBB0_784
.LBB0_798:
	s_waitcnt lgkmcnt(0)
	global_load_dwordx4 v[50:53], v[60:61], off
	s_waitcnt vmcnt(0)
	s_and_b64 vcc, exec, s[10:11]
	v_lshl_add_u64 v[56:57], v[142:143], 0, v[56:57]
	s_cbranch_vccz .LBB0_785
.LBB0_799:
	v_mov_b32_e32 v50, 0
	s_and_b64 vcc, exec, s[8:9]
	s_mov_b64 s[64:65], -1
	s_cbranch_vccz .LBB0_786
	s_branch .LBB0_787
.LBB0_800:
	global_load_dwordx4 v[46:49], v[60:61], off offset:64
	s_waitcnt vmcnt(0)
	s_and_b64 vcc, exec, s[10:11]
	s_cbranch_vccz .LBB0_789
	s_branch .LBB0_790
.LBB0_801:
	v_mov_b64_e32 v[44:45], v[236:237]
	v_lshlrev_b32_e32 v42, 16, v44
	v_and_b32_e32 v43, 0xffff0000, v44
	v_lshlrev_b32_e32 v44, 16, v45
	v_and_b32_e32 v45, 0xffff0000, v45
	s_cbranch_execnz .LBB0_792
.LBB0_802:
	global_load_dwordx4 v[42:45], v[60:61], off offset:512
	s_waitcnt vmcnt(0)
	s_and_b64 vcc, exec, s[10:11]
	s_cbranch_vccz .LBB0_793
	s_branch .LBB0_794
.LBB0_803:
	v_mov_b64_e32 v[40:41], v[238:239]
	v_lshlrev_b32_e32 v38, 16, v40
	v_and_b32_e32 v39, 0xffff0000, v40
	v_lshlrev_b32_e32 v40, 16, v41
	v_and_b32_e32 v41, 0xffff0000, v41
	s_cbranch_execnz .LBB0_796
.LBB0_804:
	global_load_dwordx4 v[38:41], v[60:61], off offset:576
	s_waitcnt vmcnt(0)
	s_and_b64 vcc, exec, s[10:11]
	s_cbranch_vccnz .LBB0_808
.LBB0_805:
	v_pk_add_f32 v[38:39], v[34:35], v[38:39]
	v_pk_add_f32 v[36:37], v[36:37], v[40:41]
	v_mul_f32_e32 v34, v39, v39
	v_fmac_f32_e32 v34, v38, v38
	v_fmac_f32_e32 v34, v36, v36
	v_fmac_f32_e32 v34, v37, v37
	v_add_f32_e32 v34, v50, v34
	ds_bpermute_b32 v35, v126, v34
	v_cvt_pk_bf16_f32 v38, v38, v39
	v_cvt_pk_bf16_f32 v39, v36, v37
	global_store_dwordx2 v[56:57], v[38:39], off offset:288
	s_waitcnt lgkmcnt(0)
	v_add_f32_e32 v34, v34, v35
	ds_bpermute_b32 v35, v0, v34
	s_and_saveexec_b64 s[64:65], s[12:13]
	s_cbranch_execz .LBB0_807
	s_waitcnt lgkmcnt(0)
	v_add_f32_e32 v34, v34, v35
	v_lshl_add_u32 v35, v54, 4, s58
	ds_write_b32 v35, v34

; template <int MODE, bool PRE = false, bool NEXT = false> ...
;     ...
;         float* orow = (float*)e.out + (long)row * e.ldo + cbase;
;         const float* arow = (const float*)e.aux + (long)row * e.ldaux + cbase;
;         const u16* brow = (const u16*)e.aux + (long)row * e.ldaux + cbase;
;         u16* xrow = e.xb + (long)row * 1024 + cbase;
;         float part = 0.f;
.LBB0_808:
	v_add_u32_e32 v38, 0xa0, v138
	v_ashrrev_i32_e32 v39, 31, v38
	v_lshlrev_b64 v[40:41], 11, v[38:39]
	v_lshl_add_u64 v[42:43], v[140:141], 0, v[40:41]
	s_and_b64 vcc, exec, s[8:9]
	s_mov_b64 s[64:65], -1
	s_cbranch_vccz .LBB0_823
	v_lshlrev_b64 v[44:45], 12, v[38:39]
	s_andn2_b64 vcc, exec, s[64:65]
	v_lshl_add_u64 v[44:45], v[136:137], 0, v[44:45]
	s_cbranch_vccz .LBB0_824

; __device__ __forceinline__ float bflo(unsigned w) { return __uint_as_float(w << 16); }
; __device__ __forceinline__ float bfhi(unsigned w) { return __uint_as_float(w & 0xffff0000u); }
; template <int MODE, bool PRE = false, bool NEXT = false> ...
;     ...
;             if (e.auxbf) { const u32x2 w = *reinterpret_cast<const u32x2*>(brow + bj * 128 + n * 16); a = f32x4{bflo(w[0]), bfhi(w[0]), bflo(w[1]), bfhi(w[1])}; }
;             else a = *reinterpret_cast<const f32x4*>(arow + bj * 128 + n * 16);
;             a += acc[ai][bj][m][n];
;             if (e.out) *reinterpret_cast<f32x4*>(orow + bj * 128 + n * 16) = a;
;             if (e.xb) {
;               u32x2 w = {cvtpk(a[0], a[1]), cvtpk(a[2], a[3])};
;               *reinterpret_cast<u32x2*>(xrow + bj * 128 + n * 16) = w;
;               part += a[0] * a[0] + a[1] * a[1] + a[2] * a[2] + a[3] * a[3];
.LBB0_811:
	s_waitcnt lgkmcnt(0)
	v_pk_add_f32 v[30:31], v[30:31], v[34:35]
	v_pk_add_f32 v[32:33], v[32:33], v[36:37]
	v_cvt_pk_bf16_f32 v34, v30, v31
	v_pk_mul_f32 v[30:31], v[30:31], v[30:31]
	v_cvt_pk_bf16_f32 v35, v32, v33
	v_pk_mul_f32 v[32:33], v[32:33], v[32:33]
	v_add_f32_e32 v30, v30, v31
	v_add_f32_e32 v30, v32, v30
	global_store_dwordx2 v[40:41], v[34:35], off
	v_add_f32_e32 v34, v33, v30
	s_and_b64 vcc, exec, s[8:9]
	s_mov_b64 s[64:65], -1
	s_cbranch_vccnz .LBB0_813
.LBB0_812:
	v_mov_b64_e32 v[32:33], v[242:243]
	s_mov_b64 s[64:65], 0
	v_lshlrev_b32_e32 v30, 16, v32
	v_and_b32_e32 v31, 0xffff0000, v32
	v_lshlrev_b32_e32 v32, 16, v33
	v_and_b32_e32 v33, 0xffff0000, v33

; template <int MODE, bool PRE = false, bool NEXT = false> ...
;     ...
;             a += acc[ai][bj][m][n];
;             if (e.out) *reinterpret_cast<f32x4*>(orow + bj * 128 + n * 16) = a;
;             if (e.xb) {
;               u32x2 w = {cvtpk(a[0], a[1]), cvtpk(a[2], a[3])};
;               *reinterpret_cast<u32x2*>(xrow + bj * 128 + n * 16) = w;
;               part += a[0] * a[0] + a[1] * a[1] + a[2] * a[2] + a[3] * a[3];
.LBB0_815:
	v_pk_add_f32 v[26:27], v[26:27], v[30:31]
	v_pk_add_f32 v[28:29], v[28:29], v[32:33]
	v_cvt_pk_bf16_f32 v30, v26, v27
	v_pk_mul_f32 v[26:27], v[26:27], v[26:27]
	v_cvt_pk_bf16_f32 v31, v28, v29
	v_pk_mul_f32 v[28:29], v[28:29], v[28:29]
	v_add_f32_e32 v26, v26, v27
	v_add_f32_e32 v26, v28, v26
	v_add_f32_e32 v26, v29, v26
	v_add_f32_e32 v34, v34, v26
	global_store_dwordx2 v[40:41], v[30:31], off offset:32

; template <int MODE, bool PRE = false, bool NEXT = false> ...
;     ...
;             a += acc[ai][bj][m][n];
;             if (e.out) *reinterpret_cast<f32x4*>(orow + bj * 128 + n * 16) = a;
;             if (e.xb) {
;               u32x2 w = {cvtpk(a[0], a[1]), cvtpk(a[2], a[3])};
;               *reinterpret_cast<u32x2*>(xrow + bj * 128 + n * 16) = w;
;               part += a[0] * a[0] + a[1] * a[1] + a[2] * a[2] + a[3] * a[3];
.LBB0_819:
	v_pk_add_f32 v[22:23], v[22:23], v[26:27]
	v_pk_add_f32 v[24:25], v[24:25], v[28:29]
	v_cvt_pk_bf16_f32 v26, v22, v23
	v_pk_mul_f32 v[22:23], v[22:23], v[22:23]
	v_cvt_pk_bf16_f32 v27, v24, v25
	v_pk_mul_f32 v[24:25], v[24:25], v[24:25]
	v_add_f32_e32 v22, v22, v23
	v_add_f32_e32 v22, v24, v22
	v_add_f32_e32 v22, v25, v22
	v_add_f32_e32 v34, v34, v22
	global_store_dwordx2 v[40:41], v[26:27], off offset:256

; __device__ __forceinline__ float bflo(unsigned w) { return __uint_as_float(w << 16); }
; __device__ __forceinline__ float bfhi(unsigned w) { return __uint_as_float(w & 0xffff0000u); }
; template <int MODE, bool PRE = false, bool NEXT = false> ...
;     ...
;             if (e.auxbf) { const u32x2 w = *reinterpret_cast<const u32x2*>(brow + bj * 128 + n * 16); a = f32x4{bflo(w[0]), bfhi(w[0]), bflo(w[1]), bfhi(w[1])}; }
;             else a = *reinterpret_cast<const f32x4*>(arow + bj * 128 + n * 16);
;             a += acc[ai][bj][m][n];
;             if (e.out) *reinterpret_cast<f32x4*>(orow + bj * 128 + n * 16) = a;
;             if (e.xb) {
;               u32x2 w = {cvtpk(a[0], a[1]), cvtpk(a[2], a[3])};
;               *reinterpret_cast<u32x2*>(xrow + bj * 128 + n * 16) = w;
;               part += a[0] * a[0] + a[1] * a[1] + a[2] * a[2] + a[3] * a[3];
;             }
;           }
;         if (e.xb) {
;           part += __int_as_float(__builtin_amdgcn_ds_bpermute((lane ^ 16) << 2, __float_as_int(part)));
;           part += __int_as_float(__builtin_amdgcn_ds_bpermute((lane ^ 32) << 2, __float_as_int(part)));
;           if (fq == 0) reinterpret_cast<float*>(g_lds)[row * 4 + wc] = part;
.LBB0_823:
	v_mov_b64_e32 v[36:37], v[240:241]
	v_lshlrev_b32_e32 v34, 16, v36
	s_waitcnt lgkmcnt(0)
	v_and_b32_e32 v35, 0xffff0000, v36
	v_lshlrev_b32_e32 v36, 16, v37
	v_and_b32_e32 v37, 0xffff0000, v37
	v_lshlrev_b64 v[44:45], 12, v[38:39]
	v_lshl_add_u64 v[44:45], v[136:137], 0, v[44:45]
	s_cbranch_execnz .LBB0_810
.LBB0_824:
	s_waitcnt lgkmcnt(0)
	global_load_dwordx4 v[34:37], v[44:45], off
	s_waitcnt vmcnt(0)
	s_and_b64 vcc, exec, s[10:11]
	v_lshl_add_u64 v[40:41], v[142:143], 0, v[40:41]
	s_cbranch_vccz .LBB0_811
.LBB0_825:
	v_mov_b32_e32 v34, 0
	s_and_b64 vcc, exec, s[8:9]
	s_mov_b64 s[64:65], -1
	s_cbranch_vccz .LBB0_812
	s_branch .LBB0_813
.LBB0_826:
	global_load_dwordx4 v[30:33], v[44:45], off offset:64
	s_waitcnt vmcnt(0)
	s_and_b64 vcc, exec, s[10:11]
	s_cbranch_vccz .LBB0_815
	s_branch .LBB0_816
.LBB0_827:
	v_mov_b64_e32 v[28:29], v[244:245]
	v_lshlrev_b32_e32 v26, 16, v28
	v_and_b32_e32 v27, 0xffff0000, v28
	v_lshlrev_b32_e32 v28, 16, v29
	v_and_b32_e32 v29, 0xffff0000, v29
	s_cbranch_execnz .LBB0_818
.LBB0_828:
	global_load_dwordx4 v[26:29], v[44:45], off offset:512
	s_waitcnt vmcnt(0)
	s_and_b64 vcc, exec, s[10:11]
	s_cbranch_vccz .LBB0_819
	s_branch .LBB0_820
.LBB0_829:
	v_mov_b64_e32 v[24:25], v[246:247]
	v_lshlrev_b32_e32 v22, 16, v24
	v_and_b32_e32 v23, 0xffff0000, v24
	v_lshlrev_b32_e32 v24, 16, v25
	v_and_b32_e32 v25, 0xffff0000, v25
	s_cbranch_execnz .LBB0_822
.LBB0_830:
	global_load_dwordx4 v[22:25], v[44:45], off offset:576
	s_waitcnt vmcnt(0)
	s_and_b64 vcc, exec, s[10:11]
	s_cbranch_vccnz .LBB0_834
.LBB0_831:
	v_pk_add_f32 v[22:23], v[18:19], v[22:23]
	v_pk_add_f32 v[20:21], v[20:21], v[24:25]
	v_mul_f32_e32 v18, v23, v23
	v_fmac_f32_e32 v18, v22, v22
	v_fmac_f32_e32 v18, v20, v20
	v_fmac_f32_e32 v18, v21, v21
	v_add_f32_e32 v18, v34, v18
	ds_bpermute_b32 v19, v126, v18
	v_cvt_pk_bf16_f32 v22, v22, v23
	v_cvt_pk_bf16_f32 v23, v20, v21
	global_store_dwordx2 v[40:41], v[22:23], off offset:288
	s_waitcnt lgkmcnt(0)
	v_add_f32_e32 v18, v18, v19
	ds_bpermute_b32 v19, v0, v18
	s_and_saveexec_b64 s[64:65], s[12:13]
	s_cbranch_execz .LBB0_833
	s_waitcnt lgkmcnt(0)
	v_add_f32_e32 v18, v18, v19
	v_lshl_add_u32 v19, v38, 4, s58
	ds_write_b32 v19, v18

; template <int MODE, bool PRE = false, bool NEXT = false> ...
;     ...
;         float* orow = (float*)e.out + (long)row * e.ldo + cbase;
;         const float* arow = (const float*)e.aux + (long)row * e.ldaux + cbase;
;         const u16* brow = (const u16*)e.aux + (long)row * e.ldaux + cbase;
;         u16* xrow = e.xb + (long)row * 1024 + cbase;
;         float part = 0.f;
.LBB0_834:
	v_add_u32_e32 v22, 0xb0, v138
	v_ashrrev_i32_e32 v23, 31, v22
	v_lshlrev_b64 v[24:25], 11, v[22:23]
	v_lshl_add_u64 v[26:27], v[140:141], 0, v[24:25]
	s_and_b64 vcc, exec, s[8:9]
	s_mov_b64 s[64:65], -1
	s_cbranch_vccz .LBB0_849
	v_lshlrev_b64 v[28:29], 12, v[22:23]
	s_andn2_b64 vcc, exec, s[64:65]
	v_lshl_add_u64 v[28:29], v[136:137], 0, v[28:29]
	s_cbranch_vccz .LBB0_850

; __device__ __forceinline__ float bflo(unsigned w) { return __uint_as_float(w << 16); }
; __device__ __forceinline__ float bfhi(unsigned w) { return __uint_as_float(w & 0xffff0000u); }
; template <int MODE, bool PRE = false, bool NEXT = false> ...
;     ...
;             if (e.auxbf) { const u32x2 w = *reinterpret_cast<const u32x2*>(brow + bj * 128 + n * 16); a = f32x4{bflo(w[0]), bfhi(w[0]), bflo(w[1]), bfhi(w[1])}; }
;             else a = *reinterpret_cast<const f32x4*>(arow + bj * 128 + n * 16);
;             a += acc[ai][bj][m][n];
;             if (e.out) *reinterpret_cast<f32x4*>(orow + bj * 128 + n * 16) = a;
;             if (e.xb) {
;               u32x2 w = {cvtpk(a[0], a[1]), cvtpk(a[2], a[3])};
;               *reinterpret_cast<u32x2*>(xrow + bj * 128 + n * 16) = w;
;               part += a[0] * a[0] + a[1] * a[1] + a[2] * a[2] + a[3] * a[3];
.LBB0_837:
	s_waitcnt lgkmcnt(0)
	v_pk_add_f32 v[14:15], v[14:15], v[18:19]
	v_pk_add_f32 v[16:17], v[16:17], v[20:21]
	v_cvt_pk_bf16_f32 v18, v14, v15
	v_pk_mul_f32 v[14:15], v[14:15], v[14:15]
	v_cvt_pk_bf16_f32 v19, v16, v17
	v_pk_mul_f32 v[16:17], v[16:17], v[16:17]
	v_add_f32_e32 v14, v14, v15
	v_add_f32_e32 v14, v16, v14
	global_store_dwordx2 v[24:25], v[18:19], off
	v_add_f32_e32 v18, v17, v14
	s_and_b64 vcc, exec, s[8:9]
	s_mov_b64 s[64:65], -1
	s_cbranch_vccnz .LBB0_839
.LBB0_838:
	v_mov_b64_e32 v[16:17], v[250:251]
	s_mov_b64 s[64:65], 0
	v_lshlrev_b32_e32 v14, 16, v16
	v_and_b32_e32 v15, 0xffff0000, v16
	v_lshlrev_b32_e32 v16, 16, v17
	v_and_b32_e32 v17, 0xffff0000, v17

; template <int MODE, bool PRE = false, bool NEXT = false> ...
;     ...
;             a += acc[ai][bj][m][n];
;             if (e.out) *reinterpret_cast<f32x4*>(orow + bj * 128 + n * 16) = a;
;             if (e.xb) {
;               u32x2 w = {cvtpk(a[0], a[1]), cvtpk(a[2], a[3])};
;               *reinterpret_cast<u32x2*>(xrow + bj * 128 + n * 16) = w;
;               part += a[0] * a[0] + a[1] * a[1] + a[2] * a[2] + a[3] * a[3];
.LBB0_841:
	v_pk_add_f32 v[10:11], v[10:11], v[14:15]
	v_pk_add_f32 v[12:13], v[12:13], v[16:17]
	v_cvt_pk_bf16_f32 v14, v10, v11
	v_pk_mul_f32 v[10:11], v[10:11], v[10:11]
	v_cvt_pk_bf16_f32 v15, v12, v13
	v_pk_mul_f32 v[12:13], v[12:13], v[12:13]
	v_add_f32_e32 v10, v10, v11
	v_add_f32_e32 v10, v12, v10
	v_add_f32_e32 v10, v13, v10
	v_add_f32_e32 v18, v18, v10
	global_store_dwordx2 v[24:25], v[14:15], off offset:32

; template <int MODE, bool PRE = false, bool NEXT = false> ...
;     ...
;             a += acc[ai][bj][m][n];
;             if (e.out) *reinterpret_cast<f32x4*>(orow + bj * 128 + n * 16) = a;
;             if (e.xb) {
;               u32x2 w = {cvtpk(a[0], a[1]), cvtpk(a[2], a[3])};
;               *reinterpret_cast<u32x2*>(xrow + bj * 128 + n * 16) = w;
;               part += a[0] * a[0] + a[1] * a[1] + a[2] * a[2] + a[3] * a[3];
.LBB0_845:
	v_pk_add_f32 v[6:7], v[6:7], v[10:11]
	v_pk_add_f32 v[8:9], v[8:9], v[12:13]
	v_cvt_pk_bf16_f32 v10, v6, v7
	v_pk_mul_f32 v[6:7], v[6:7], v[6:7]
	v_cvt_pk_bf16_f32 v11, v8, v9
	v_pk_mul_f32 v[8:9], v[8:9], v[8:9]
	v_add_f32_e32 v6, v6, v7
	v_add_f32_e32 v6, v8, v6
	v_add_f32_e32 v6, v9, v6
	v_add_f32_e32 v18, v18, v6
	global_store_dwordx2 v[24:25], v[10:11], off offset:256

; __device__ __forceinline__ float bflo(unsigned w) { return __uint_as_float(w << 16); }
; __device__ __forceinline__ float bfhi(unsigned w) { return __uint_as_float(w & 0xffff0000u); }
; template <int MODE, bool PRE = false, bool NEXT = false> ...
;     ...
;             if (e.auxbf) { const u32x2 w = *reinterpret_cast<const u32x2*>(brow + bj * 128 + n * 16); a = f32x4{bflo(w[0]), bfhi(w[0]), bflo(w[1]), bfhi(w[1])}; }
;             else a = *reinterpret_cast<const f32x4*>(arow + bj * 128 + n * 16);
;             a += acc[ai][bj][m][n];
;             if (e.out) *reinterpret_cast<f32x4*>(orow + bj * 128 + n * 16) = a;
;             if (e.xb) {
;               u32x2 w = {cvtpk(a[0], a[1]), cvtpk(a[2], a[3])};
;               *reinterpret_cast<u32x2*>(xrow + bj * 128 + n * 16) = w;
;               part += a[0] * a[0] + a[1] * a[1] + a[2] * a[2] + a[3] * a[3];
;             }
;           }
;         if (e.xb) {
;           part += __int_as_float(__builtin_amdgcn_ds_bpermute((lane ^ 16) << 2, __float_as_int(part)));
;           part += __int_as_float(__builtin_amdgcn_ds_bpermute((lane ^ 32) << 2, __float_as_int(part)));
;           if (fq == 0) reinterpret_cast<float*>(g_lds)[row * 4 + wc] = part;
.LBB0_849:
	v_mov_b64_e32 v[20:21], v[248:249]
	v_lshlrev_b32_e32 v18, 16, v20
	s_waitcnt lgkmcnt(0)
	v_and_b32_e32 v19, 0xffff0000, v20
	v_lshlrev_b32_e32 v20, 16, v21
	v_and_b32_e32 v21, 0xffff0000, v21
	v_lshlrev_b64 v[28:29], 12, v[22:23]
	v_lshl_add_u64 v[28:29], v[136:137], 0, v[28:29]
	s_cbranch_execnz .LBB0_836
.LBB0_850:
	s_waitcnt lgkmcnt(0)
	global_load_dwordx4 v[18:21], v[28:29], off
	s_waitcnt vmcnt(0)
	s_and_b64 vcc, exec, s[10:11]
	v_lshl_add_u64 v[24:25], v[142:143], 0, v[24:25]
	s_cbranch_vccz .LBB0_837
.LBB0_851:
	v_mov_b32_e32 v18, 0
	s_and_b64 vcc, exec, s[8:9]
	s_mov_b64 s[64:65], -1
	s_cbranch_vccz .LBB0_838
	s_branch .LBB0_839
.LBB0_852:
	global_load_dwordx4 v[14:17], v[28:29], off offset:64
	s_waitcnt vmcnt(0)
	s_and_b64 vcc, exec, s[10:11]
	s_cbranch_vccz .LBB0_841
	s_branch .LBB0_842
.LBB0_853:
	v_mov_b64_e32 v[12:13], v[182:183]
	v_lshlrev_b32_e32 v10, 16, v12
	v_and_b32_e32 v11, 0xffff0000, v12
	v_lshlrev_b32_e32 v12, 16, v13
	v_and_b32_e32 v13, 0xffff0000, v13
	s_cbranch_execnz .LBB0_844
.LBB0_854:
	global_load_dwordx4 v[10:13], v[28:29], off offset:512
	s_waitcnt vmcnt(0)
	s_and_b64 vcc, exec, s[10:11]
	s_cbranch_vccz .LBB0_845
	s_branch .LBB0_846
.LBB0_855:
	v_mov_b64_e32 v[8:9], v[184:185]
	v_lshlrev_b32_e32 v6, 16, v8
	v_and_b32_e32 v7, 0xffff0000, v8
	v_lshlrev_b32_e32 v8, 16, v9
	v_and_b32_e32 v9, 0xffff0000, v9
	s_cbranch_execnz .LBB0_848
.LBB0_856:
	global_load_dwordx4 v[6:9], v[28:29], off offset:576
	s_waitcnt vmcnt(0)
	s_and_b64 vcc, exec, s[10:11]
	s_cbranch_vccnz .LBB0_642
.LBB0_857:
	v_pk_add_f32 v[6:7], v[2:3], v[6:7]
	v_pk_add_f32 v[4:5], v[4:5], v[8:9]
	v_mul_f32_e32 v2, v7, v7
	v_fmac_f32_e32 v2, v6, v6
	v_fmac_f32_e32 v2, v4, v4
	v_fmac_f32_e32 v2, v5, v5
	v_add_f32_e32 v2, v18, v2
	ds_bpermute_b32 v3, v126, v2
	v_cvt_pk_bf16_f32 v6, v6, v7
	v_cvt_pk_bf16_f32 v7, v4, v5
	global_store_dwordx2 v[24:25], v[6:7], off offset:288
	s_waitcnt lgkmcnt(0)
	v_add_f32_e32 v2, v2, v3
	ds_bpermute_b32 v0, v0, v2
	s_and_saveexec_b64 s[8:9], s[12:13]
	s_cbranch_execz .LBB0_859
	s_waitcnt lgkmcnt(0)
	v_add_f32_e32 v0, v2, v0
	v_lshl_add_u32 v2, v22, 4, s58
	ds_write_b32 v2, v0
